# attention work queue: next dynamic item requested at the end of the key loop (atomic round trip beside the item epilogue) instead of between the two barriers at the loop head
# speedup vs baseline: 1.0037x; 1.0000x over previous
.LBB0_429:
	s_andn2_b64 vcc, exec, s[20:21]
	s_cbranch_vccnz .LBB0_478
	v_mov_b32_e32 v3, v202
	s_ashr_i32 s17, s16, 31
	v_and_b32_e32 v0, 63, v3
	s_lshl_b64 s[20:21], s[16:17], 2
	v_readlane_b32 s8, v254, 59
	v_lshl_or_b32 v6, s18, 6, v0
	s_add_u32 s90, s8, s20
	v_readlane_b32 s8, v254, 60
	v_ashrrev_i32_e32 v7, 31, v6
	s_addc_u32 s91, s8, s21
	v_lshlrev_b64 v[6:7], 2, v[6:7]
	v_readlane_b32 s20, v254, 63
	v_lshl_add_u64 v[8:9], s[62:63], 0, v[6:7]
	v_readlane_b32 s21, v255, 0
	global_load_dword v4, v[8:9], off
	v_readlane_b32 s22, v255, 1
	v_lshl_add_u64 v[8:9], s[20:21], 0, v[6:7]
	global_load_dword v10, v[8:9], off
	v_readlane_b32 s23, v255, 2
	v_readlane_b32 s24, v255, 3
	v_readlane_b32 s25, v255, 4
	v_lshl_add_u64 v[8:9], s[22:23], 0, v[6:7]
	global_load_dword v8, v[8:9], off
	v_lshl_add_u64 v[6:7], s[24:25], 0, v[6:7]
	global_load_dword v6, v[6:7], off
	v_cmp_lt_i32_e32 vcc, v209, v208
	s_ashr_i32 s19, s18, 31
	s_lshl_b64 s[20:21], s[18:19], 2
	v_cndmask_b32_e32 v9, v207, v209, vcc
	v_lshlrev_b32_e32 v166, 2, v9
	v_cmp_lt_i32_e32 vcc, v210, v208
	v_readlane_b32 s22, v253, 1
	v_readlane_b32 s23, v253, 2
	s_add_u32 s20, s22, s20
	s_addc_u32 s21, s23, s21
	s_load_dword s8, s[20:21], 0x100
	v_ashrrev_i32_e32 v2, 6, v3
	s_movk_i32 s20, 0x2200
	v_and_b32_e32 v168, 3, v2
	v_mul_lo_u32 v2, v2, s20
	v_and_b32_e32 v135, 31, v3
	v_bfe_u32 v5, v3, 5, 1
	s_movk_i32 s23, 0x90
	v_lshlrev_b32_e32 v134, 3, v5
	s_movk_i32 s20, 0x100
	v_cmp_gt_u32_e64 s[44:45], s20, v3
	s_lshl_b32 s20, s18, 7
	s_mul_i32 s22, s18, 0x1200000
	s_lshl_b32 s19, s18, 3
	s_ashr_i32 s21, s20, 31
	s_waitcnt lgkmcnt(0)
	v_sub_f32_e64 v167, 1.0, s8
	v_readlane_b32 s26, v255, 5
	v_readlane_b32 s27, v255, 6
	s_mov_b32 s17, 0
	s_mov_b32 s32, 0
	v_cmp_eq_u32_e64 s[40:41], 0, v3
	v_lshlrev_b32_e32 v170, 5, v168
	s_movk_i32 s88, 0x90
	v_mov_b32_e32 v139, v1
	s_movk_i32 s89, 0x600
	v_mov_b32_e32 v143, v1
	s_waitcnt vmcnt(2)
	v_mul_f32_e32 v11, v4, v10
	ds_bpermute_b32 v9, v166, v11
	s_waitcnt lgkmcnt(0)
	v_fmac_f32_e32 v9, v4, v10
	s_waitcnt vmcnt(0)
	v_mul_f32_e32 v7, v8, v6
	v_cndmask_b32_e32 v4, v207, v210, vcc
	ds_bpermute_b32 v7, v166, v7
	v_lshlrev_b32_e32 v4, 2, v4
	ds_bpermute_b32 v10, v4, v9
	v_cmp_lt_i32_e32 vcc, v211, v208
	s_waitcnt lgkmcnt(1)
	v_fmac_f32_e32 v7, v8, v6
	ds_bpermute_b32 v4, v4, v7
	s_waitcnt lgkmcnt(1)
	v_add_f32_e32 v9, v9, v10
	v_cndmask_b32_e32 v10, v207, v211, vcc
	v_lshlrev_b32_e32 v10, 2, v10
	ds_bpermute_b32 v11, v10, v9
	s_waitcnt lgkmcnt(1)
	v_add_f32_e32 v4, v7, v4
	ds_bpermute_b32 v6, v10, v4
	v_cmp_lt_i32_e32 vcc, v212, v208
	v_ashrrev_i32_e32 v10, 8, v3
	s_waitcnt lgkmcnt(1)
	v_add_f32_e32 v9, v9, v11
	v_cndmask_b32_e32 v11, v207, v212, vcc
	v_lshlrev_b32_e32 v11, 2, v11
	ds_bpermute_b32 v12, v11, v9
	s_waitcnt lgkmcnt(1)
	v_add_f32_e32 v4, v4, v6
	ds_bpermute_b32 v6, v11, v4
	v_cmp_lt_i32_e32 vcc, v213, v208
	v_lshlrev_b32_e32 v171, 6, v10
	s_waitcnt lgkmcnt(1)
	v_add_f32_e32 v9, v9, v12
	v_cndmask_b32_e32 v12, v207, v213, vcc
	v_lshlrev_b32_e32 v12, 2, v12
	ds_bpermute_b32 v13, v12, v9
	s_waitcnt lgkmcnt(1)
	v_add_f32_e32 v4, v4, v6
	ds_bpermute_b32 v6, v12, v4
	v_cmp_lt_i32_e32 vcc, v214, v208
	v_lshlrev_b32_e32 v172, 7, v10
	s_waitcnt lgkmcnt(1)
	v_add_f32_e32 v9, v9, v13
	v_cndmask_b32_e32 v13, v207, v214, vcc
	v_lshlrev_b32_e32 v13, 2, v13
	s_waitcnt lgkmcnt(0)
	v_add_f32_e32 v4, v4, v6
	ds_bpermute_b32 v14, v13, v9
	ds_bpermute_b32 v6, v13, v4
	v_cmp_gt_u32_e32 vcc, 32, v0
	v_lshlrev_b32_e32 v0, 2, v0
	v_cmp_eq_u32_e64 s[42:43], 1, v10
	s_waitcnt lgkmcnt(1)
	v_add_f32_e32 v9, v9, v14
	s_waitcnt lgkmcnt(0)
	v_add_f32_e32 v4, v4, v6
	v_mul_f32_e32 v6, 0x3fb8aa3b, v9
	v_mul_f32_e32 v4, 0x3fb8aa3b, v4
	v_exp_f32_e32 v6, v6
	v_exp_f32_e32 v4, v4
	v_lshl_or_b32 v173, v168, 14, v0
	v_lshrrev_b32_e32 v13, 4, v3
	v_bfe_u32 v11, v3, 4, 2
	v_sub_f32_e32 v4, v6, v4
	v_add_f32_e32 v132, s8, v4
	v_lshlrev_b32_e32 v4, 3, v3
	v_add_u32_e32 v6, 0x10000, v2
	v_and_b32_e32 v2, 56, v4
	v_and_b32_e32 v4, 0x78, v4
	v_mad_u32_u24 v9, v135, s23, v6
	v_lshl_or_b32 v8, v2, 1, v6
	v_mad_u32_u24 v10, v135, s83, v6
	v_lshl_or_b32 v0, v4, 1, v6
	v_bfe_u32 v6, v3, 3, 3
	v_mad_u32_u24 v175, v6, s23, v8
	v_or_b32_e32 v179, v10, v134
	v_or_b32_e32 v10, 12, v13
	s_movk_i32 s23, 0x600
	v_mad_u64_u32 v[136:137], s[24:25], v10, s83, v[0:1]
	v_mul_lo_u32 v138, v10, s23
	v_mov_b32_e32 v10, 0x7800
	v_mov_b32_e32 v12, 0x9000
	v_mad_u32_u24 v180, v11, s83, v0
	v_mul_u32_u24_e32 v8, 0x600, v11
	v_mad_u32_u24 v10, v11, s23, v10
	v_mad_u32_u24 v12, v11, s23, v12
	v_or_b32_e32 v11, 28, v13
	v_mad_u64_u32 v[140:141], s[24:25], v11, s83, v[0:1]
	v_readlane_b32 s24, v254, 30
	s_mul_hi_i32 s8, s18, 0x1200000
	v_readlane_b32 s25, v254, 31
	s_add_u32 s31, s24, s22
	s_addc_u32 s34, s25, s8
	s_add_u32 s22, s14, s22
	s_addc_u32 s8, s15, s8
	s_add_u32 s35, s22, 0x11fb8000
	s_addc_u32 s36, s8, 0
	s_lshl_b64 s[20:21], s[20:21], 2
	s_add_u32 s20, s26, s20
	v_ashrrev_i32_e32 v7, 3, v3
	v_mul_u32_u24_e32 v6, 0x600, v6
	s_addc_u32 s21, s27, s21
	v_lshlrev_b32_e32 v0, 4, v5
	s_movk_i32 s8, 0xffe0
	v_and_b32_e32 v169, 0xffffffe0, v7
	v_cndmask_b32_e64 v174, 0, 1.0, vcc
	v_add_u32_e32 v176, 0x480, v175
	v_add_u32_e32 v177, 0x900, v175
	v_add_u32_e32 v178, 0xd80, v175
	v_add_u32_e32 v181, 0x440, v180
	v_add_u32_e32 v182, 0x880, v180
	v_add_u32_e32 v137, 0x1100, v180
	v_add_u32_e32 v183, 0x1540, v180
	v_add_u32_e32 v184, 0x1980, v180
	v_mul_lo_u32 v142, v11, s23
	v_lshl_add_u64 v[144:145], s[20:21], 0, v[0:1]
	v_mov_b32_e32 v133, v132
	v_bfi_b32 v141, s8, v7, v3
	v_lshlrev_b32_e32 v146, 1, v2
	v_lshlrev_b32_e32 v148, 1, v6
	v_lshlrev_b32_e32 v150, 1, v4
	v_lshlrev_b32_e32 v152, 1, v8
	v_lshlrev_b32_e32 v154, 1, v10
	v_lshlrev_b32_e32 v156, 1, v12
	v_add_u32_e32 v185, v9, v134
	s_branch .LBB0_434
.Lat_pf_use:
	s_mov_b32 s32, 0
	s_waitcnt vmcnt(0)
	v_readfirstlane_b32 s8, v250
	v_readlane_b32 s22, v255, 9
	s_nop 3
	s_add_i32 s8, s22, s8
	v_mov_b32_e32 v0, s8
	s_branch .LBB0_440

.LBB0_434:
	s_barrier
	s_and_saveexec_b64 s[20:21], s[40:41]
	s_cbranch_execz .LBB0_441
	s_cmp_eq_u32 s17, 0
	v_readlane_b32 s24, v255, 7
	s_cselect_b64 s[22:23], -1, 0
	v_readlane_b32 s25, v255, 8
	s_and_b64 s[22:23], s[24:25], s[22:23]
	v_readlane_b32 s8, v255, 13
	s_and_b64 vcc, exec, s[22:23]
	s_nop 0
	v_mov_b32_e32 v0, s8
	s_cbranch_vccnz .LBB0_440
	s_cmp_eq_u32 s17, 1
	v_readlane_b32 s24, v255, 7
	s_cselect_b64 s[22:23], -1, 0
	v_readlane_b32 s25, v255, 8
	s_and_b64 s[22:23], s[24:25], s[22:23]
	v_readlane_b32 s24, v254, 61
	v_readlane_b32 s25, v254, 62
	s_and_b64 s[24:25], s[24:25], s[22:23]
	s_and_b64 s[24:25], s[24:25], exec
	v_readlane_b32 s8, v255, 10
	v_readlane_b32 s24, v255, 12
	s_cselect_b32 s8, s24, s8
	s_and_b64 vcc, exec, s[22:23]
	v_mov_b32_e32 v0, s8
	s_cbranch_vccnz .LBB0_440
	s_cmp_eq_u32 s32, 1
	s_cbranch_scc1 .Lat_pf_use
	s_mov_b64 s[24:25], exec
	v_mbcnt_lo_u32_b32 v0, s24, 0
	v_mbcnt_hi_u32_b32 v0, s25, v0
	v_cmp_eq_u32_e32 vcc, 0, v0
	s_and_saveexec_b64 s[22:23], vcc
	s_cbranch_execz .LBB0_439
	s_bcnt1_i32_b64 s8, s[24:25]
	v_mov_b32_e32 v2, s8
	global_atomic_add v2, v1, v2, s[90:91] sc0

.LBB0_467:
	s_cmp_lt_u32 s17, 1
	s_cbranch_scc1 .Lat_pfb_skip
	s_and_saveexec_b64 s[92:93], s[40:41]
	s_cbranch_execz .Lat_pfb_none
	v_mov_b32_e32 v251, 0
	v_mov_b32_e32 v250, 1
	global_atomic_add v250, v251, v250, s[90:91] sc0
	s_mov_b32 s32, 1
.Lat_pfb_none:
	s_or_b64 exec, exec, s[92:93]

.Lat_a_nowrite:
	s_waitcnt lgkmcnt(0)
	s_barrier
	s_add_i32 s25, s25, 1
	s_cmp_le_u32 s25, s26
	s_cbranch_scc1 .LBB0_470
	s_cmp_lt_u32 s17, 1
	s_cbranch_scc1 .Lat_pfa_skip
	s_and_saveexec_b64 s[92:93], s[40:41]
	s_cbranch_execz .Lat_pfa_none
	v_mov_b32_e32 v251, 0
	v_mov_b32_e32 v250, 1
	global_atomic_add v250, v251, v250, s[90:91] sc0
	s_mov_b32 s32, 1

.Lat_pfa_skip:
	v_mov_b32_e32 v0, v149
	ds_bpermute_b32 v2, v166, v0
	s_waitcnt lgkmcnt(0)
	v_add_f32_e32 v0, v0, v2
	v_div_scale_f32 v2, s[20:21], v0, v0, 1.0
	v_rcp_f32_e32 v3, v2
	s_nop 0
	v_fma_f32 v4, -v2, v3, 1.0
	v_fmac_f32_e32 v3, v4, v3
	v_div_scale_f32 v4, vcc, 1.0, v0, 1.0
	v_mul_f32_e32 v5, v4, v3
	v_fma_f32 v6, -v2, v5, v4
	v_fmac_f32_e32 v5, v6, v3
	v_fma_f32 v2, -v2, v5, v4
	v_div_fmas_f32 v2, v2, v3, v5
	v_div_fixup_f32 v0, v2, v0, 1.0
	v_pk_mul_f32 v[88:89], v[64:65], v[0:1] op_sel_hi:[1,0]
	v_pk_mul_f32 v[92:93], v[66:67], v[0:1] op_sel_hi:[1,0]
	v_pk_mul_f32 v[4:5], v[68:69], v[0:1] op_sel_hi:[1,0]
	v_pk_mul_f32 v[90:91], v[70:71], v[0:1] op_sel_hi:[1,0]
	v_pk_mul_f32 v[2:3], v[72:73], v[0:1] op_sel_hi:[1,0]
	v_pk_mul_f32 v[86:87], v[74:75], v[0:1] op_sel_hi:[1,0]
	v_pk_mul_f32 v[10:11], v[76:77], v[0:1] op_sel_hi:[1,0]
	v_pk_mul_f32 v[84:85], v[78:79], v[0:1] op_sel_hi:[1,0]
	v_pk_mul_f32 v[6:7], v[48:49], v[0:1] op_sel_hi:[1,0]
	v_pk_mul_f32 v[12:13], v[50:51], v[0:1] op_sel_hi:[1,0]
	v_pk_mul_f32 v[48:49], v[52:53], v[0:1] op_sel_hi:[1,0]
	v_pk_mul_f32 v[8:9], v[54:55], v[0:1] op_sel_hi:[1,0]
	v_pk_mul_f32 v[14:15], v[56:57], v[0:1] op_sel_hi:[1,0]
	v_pk_mul_f32 v[72:73], v[58:59], v[0:1] op_sel_hi:[1,0]
	v_pk_mul_f32 v[64:65], v[60:61], v[0:1] op_sel_hi:[1,0]
	v_pk_mul_f32 v[54:55], v[62:63], v[0:1] op_sel_hi:[1,0]
	v_pk_mul_f32 v[70:71], v[32:33], v[0:1] op_sel_hi:[1,0]
	v_pk_mul_f32 v[78:79], v[34:35], v[0:1] op_sel_hi:[1,0]
	v_pk_mul_f32 v[74:75], v[36:37], v[0:1] op_sel_hi:[1,0]
	v_pk_mul_f32 v[82:83], v[38:39], v[0:1] op_sel_hi:[1,0]
	v_pk_mul_f32 v[68:69], v[40:41], v[0:1] op_sel_hi:[1,0]
	v_pk_mul_f32 v[80:81], v[42:43], v[0:1] op_sel_hi:[1,0]
	v_pk_mul_f32 v[60:61], v[44:45], v[0:1] op_sel_hi:[1,0]
	v_pk_mul_f32 v[76:77], v[46:47], v[0:1] op_sel_hi:[1,0]
	v_pk_mul_f32 v[50:51], v[16:17], v[0:1] op_sel_hi:[1,0]
	v_pk_mul_f32 v[66:67], v[18:19], v[0:1] op_sel_hi:[1,0]
	v_pk_mul_f32 v[42:43], v[20:21], v[0:1] op_sel_hi:[1,0]
	v_pk_mul_f32 v[56:57], v[22:23], v[0:1] op_sel_hi:[1,0]
	v_pk_mul_f32 v[38:39], v[24:25], v[0:1] op_sel_hi:[1,0]
	v_pk_mul_f32 v[52:53], v[26:27], v[0:1] op_sel_hi:[1,0]
	v_pk_mul_f32 v[18:19], v[28:29], v[0:1] op_sel_hi:[1,0]
	v_pk_mul_f32 v[16:17], v[30:31], v[0:1] op_sel_hi:[1,0]
	s_and_saveexec_b64 s[20:21], s[42:43]
	s_cbranch_execz .LBB0_476
	ds_write2st64_b32 v173, v88, v89 offset1:1
	ds_write2st64_b32 v173, v92, v93 offset0:2 offset1:3
	ds_write2st64_b32 v173, v4, v5 offset0:4 offset1:5
	ds_write2st64_b32 v173, v90, v91 offset0:6 offset1:7
	ds_write2st64_b32 v173, v2, v3 offset0:8 offset1:9
	ds_write2st64_b32 v173, v86, v87 offset0:10 offset1:11
	ds_write2st64_b32 v173, v10, v11 offset0:12 offset1:13
	ds_write2st64_b32 v173, v84, v85 offset0:14 offset1:15
	ds_write2st64_b32 v173, v6, v7 offset0:16 offset1:17
	ds_write2st64_b32 v173, v12, v13 offset0:18 offset1:19
	ds_write2st64_b32 v173, v48, v49 offset0:20 offset1:21
	ds_write2st64_b32 v173, v8, v9 offset0:22 offset1:23
	ds_write2st64_b32 v173, v14, v15 offset0:24 offset1:25
	ds_write2st64_b32 v173, v72, v73 offset0:26 offset1:27
	ds_write2st64_b32 v173, v64, v65 offset0:28 offset1:29
	ds_write2st64_b32 v173, v54, v55 offset0:30 offset1:31
	ds_write2st64_b32 v173, v70, v71 offset0:32 offset1:33
	ds_write2st64_b32 v173, v78, v79 offset0:34 offset1:35
	ds_write2st64_b32 v173, v74, v75 offset0:36 offset1:37
	ds_write2st64_b32 v173, v82, v83 offset0:38 offset1:39
	ds_write2st64_b32 v173, v68, v69 offset0:40 offset1:41
	ds_write2st64_b32 v173, v80, v81 offset0:42 offset1:43
	ds_write2st64_b32 v173, v60, v61 offset0:44 offset1:45
	ds_write2st64_b32 v173, v76, v77 offset0:46 offset1:47
	ds_write2st64_b32 v173, v50, v51 offset0:48 offset1:49
	ds_write2st64_b32 v173, v66, v67 offset0:50 offset1:51
	ds_write2st64_b32 v173, v42, v43 offset0:52 offset1:53
	ds_write2st64_b32 v173, v56, v57 offset0:54 offset1:55
	ds_write2st64_b32 v173, v38, v39 offset0:56 offset1:57
	ds_write2st64_b32 v173, v52, v53 offset0:58 offset1:59
	ds_write2st64_b32 v173, v18, v19 offset0:60 offset1:61
	ds_write2st64_b32 v173, v16, v17 offset0:62 offset1:63
